# GEMM prologues of P5/P6/P7/P9: the compiler's full vmcnt(0) between the second LDS-DMA batch and the template's vmcnt(6) relaxed to a counted wait
# baseline (speedup 1.0000x reference)
.LBB0_1125:
	s_lshl_b32 s12, s12, 5
	s_and_b32 s22, s12, 0x60
	s_mov_b64 s[12:13], 0x80
	s_add_i32 m0, s37, 0x18000
	v_lshl_add_u64 v[8:9], v[8:9], 0, s[12:13]
	s_lshl_b32 s19, s1, 13
	s_lshl_b32 s23, s22, 7
	s_waitcnt vmcnt(2)
	s_barrier
	global_load_lds_dwordx4 v[8:9], off
	v_lshl_add_u64 v[4:5], v[4:5], 0, s[12:13]
	s_add_i32 m0, s37, 0x1a000
	s_add_i32 s51, s37, 0x8000
	s_add_i32 s52, s37, 0xa000
	global_load_lds_dwordx4 v[4:5], off
	v_lshl_add_u64 v[2:3], v[2:3], 0, s[12:13]
	s_mov_b32 m0, s51
	s_add_u32 s20, s40, 0x40080
	global_load_lds_dwordx4 v[2:3], off
	v_lshl_add_u64 v[2:3], v[6:7], 0, s[12:13]
	s_mov_b32 m0, s52
	s_addc_u32 s21, s41, 0
	global_load_lds_dwordx4 v[2:3], off
	s_add_i32 m0, s37, 0x1c000
	v_lshl_add_u64 v[2:3], s[20:21], 0, v[132:133]
	global_load_lds_dwordx4 v[2:3], off
	v_lshl_add_u64 v[2:3], s[20:21], 0, v[136:137]
	s_add_i32 m0, s37, 0x1e000
	v_lshlrev_b32_e32 v5, 2, v0
	global_load_lds_dwordx4 v[2:3], off
	v_and_b32_e32 v3, 24, v14
	v_and_b32_e32 v2, 15, v0
	v_lshlrev_b32_e32 v4, 1, v3
	v_lshl_or_b32 v1, s1, 6, v2
	v_lshl_or_b32 v2, v2, 6, v4
	v_and_b32_e32 v5, 32, v5
	s_sext_i32_i8 s56, s0
	v_bitop3_b32 v5, v2, s19, v5 bitop3:0xde
	v_lshlrev_b32_e32 v2, 6, v0
	s_movk_i32 s0, 0x3c0
	v_and_or_b32 v2, v2, s0, v4
	s_waitcnt vmcnt(8)
	v_and_b32_e32 v4, 32, v40
	v_bitop3_b32 v154, s23, v2, v4 bitop3:0xf6
	v_lshlrev_b32_e32 v2, 8, v0
	v_and_b32_e32 v2, 0x18000, v2
	v_lshlrev_b32_e32 v4, 11, v12
	v_or3_b32 v2, v10, v2, v4
	s_mov_b64 s[0:1], 0x40080
	v_or_b32_e32 v155, s22, v3
	v_add_u32_e32 v2, v2, v11
	v_mov_b32_e32 v3, v133
	v_lshl_add_u64 v[138:139], v[2:3], 0, s[0:1]
	v_lshlrev_b32_e32 v2, 4, v13
	v_and_b32_e32 v2, 0x38000, v2
	s_waitcnt vmcnt(6)
	s_cmpk_lt_u32 s18, 0x100
	v_or3_b32 v2, v10, v2, v4
	s_cselect_b64 s[18:19], -1, 0
	v_add_u32_e32 v2, v2, v11
	s_add_i32 s54, 0, 0x10000
	s_add_i32 s55, 0, 0x14000
	s_ashr_i32 s53, s88, 31
	v_lshl_add_u64 v[140:141], v[2:3], 0, s[0:1]
	v_mov_b64_e32 v[142:143], 0x100
	v_mov_b64_e32 v[144:145], 0xff
	v_add_u32_e32 v156, s54, v154
	v_add_u32_e32 v157, s55, v154
	v_add_u32_e32 v158, 0, v5
	s_mov_b64 s[20:21], 0x48000
	s_mov_b64 s[22:23], 0x50000
	s_mov_b64 s[24:25], 0x58000
	s_barrier
	s_branch .LBB0_1128

.LBB0_1214:
	s_mov_b64 s[20:21], 0x80
	s_and_b32 s48, s1, 3
	s_add_i32 m0, s44, 0x18000
	v_lshl_add_u64 v[8:9], v[8:9], 0, s[20:21]
	s_lshl_b32 s1, s0, 13
	s_lshl_b32 s23, s48, 12
	s_waitcnt vmcnt(2)
	s_barrier
	global_load_lds_dwordx4 v[8:9], off
	v_lshl_add_u64 v[6:7], v[6:7], 0, s[20:21]
	s_add_i32 m0, s44, 0x1a000
	s_add_i32 s49, s44, 0x8000
	s_add_i32 s50, s44, 0xa000
	global_load_lds_dwordx4 v[6:7], off
	v_lshl_add_u64 v[2:3], v[2:3], 0, s[20:21]
	s_mov_b32 m0, s49
	s_add_u32 s4, s38, 0x40080
	global_load_lds_dwordx4 v[2:3], off
	v_lshl_add_u64 v[2:3], v[4:5], 0, s[20:21]
	s_mov_b32 m0, s50
	s_addc_u32 s5, s39, 0
	global_load_lds_dwordx4 v[2:3], off
	s_add_i32 m0, s44, 0x1c000
	v_lshl_add_u64 v[2:3], s[4:5], 0, v[132:133]
	global_load_lds_dwordx4 v[2:3], off
	v_lshl_add_u64 v[2:3], s[4:5], 0, v[136:137]
	s_add_i32 m0, s44, 0x1e000
	s_waitcnt vmcnt(7)
	v_lshlrev_b32_e32 v4, 6, v43
	global_load_lds_dwordx4 v[2:3], off
	v_and_b32_e32 v2, 3, v1
	v_lshl_or_b32 v1, s0, 6, v43
	v_lshlrev_b32_e32 v5, 4, v2
	s_movk_i32 s0, 0x3c0
	v_lshlrev_b32_e32 v6, 2, v43
	v_and_or_b32 v4, v4, s0, v5
	v_and_b32_e32 v6, 32, v6
	v_bitop3_b32 v4, v4, s1, v6 bitop3:0xde
	v_lshlrev_b32_e32 v6, 6, v0
	v_lshlrev_b32_e32 v3, 3, v2
	v_and_or_b32 v5, v6, s0, v5
	v_and_b32_e32 v6, 32, v42
	v_cmp_eq_u32_e64 s[0:1], 0, v2
	v_lshlrev_b32_e32 v2, 8, v0
	v_bitop3_b32 v152, s23, v5, v6 bitop3:0xf6
	v_and_b32_e32 v2, 0x18000, v2
	v_lshlrev_b32_e32 v5, 11, v12
	v_or3_b32 v2, v10, v2, v5
	s_mov_b64 s[4:5], 0x40080
	v_lshl_or_b32 v153, s48, 5, v3
	v_add_u32_e32 v2, v2, v11
	v_mov_b32_e32 v3, v133
	v_lshl_add_u64 v[138:139], v[2:3], 0, s[4:5]
	v_lshlrev_b32_e32 v2, 4, v13
	v_and_b32_e32 v2, 0x38000, v2
	v_or3_b32 v2, v10, v2, v5
	s_waitcnt vmcnt(6)
	s_cmpk_lt_u32 s22, 0x100
	v_add_u32_e32 v2, v2, v11
	s_cselect_b64 s[22:23], -1, 0
	v_lshl_add_u64 v[140:141], v[2:3], 0, s[4:5]
	s_add_i32 s53, 0, 0x10000
	s_add_i32 s54, 0, 0x14000
	v_mbcnt_lo_u32_b32 v2, -1, 0
	s_ashr_i32 s51, s88, 31
	s_ashr_i32 s52, s2, 31
	v_mov_b64_e32 v[142:143], 0x100
	v_mov_b64_e32 v[144:145], 0xff
	v_add_u32_e32 v154, s53, v152
	v_add_u32_e32 v155, s54, v152
	v_add_u32_e32 v156, 0, v4
	v_mbcnt_hi_u32_b32 v157, -1, v2
	s_mov_b32 s55, 0
	s_barrier
	s_branch .LBB0_1217

.LBB0_1313:
	s_lshl_b32 s5, s12, 5
	s_mov_b64 s[12:13], 0x80
	s_and_b32 s22, s5, 0x60
	s_add_i32 m0, s39, 0x18000
	v_lshl_add_u64 v[8:9], v[8:9], 0, s[12:13]
	s_lshl_b32 s19, s1, 13
	s_lshl_b32 s23, s22, 7
	s_waitcnt vmcnt(2)
	s_barrier
	global_load_lds_dwordx4 v[8:9], off
	v_lshl_add_u64 v[6:7], v[6:7], 0, s[12:13]
	s_add_i32 m0, s39, 0x1a000
	s_add_i32 s44, s39, 0x8000
	s_add_i32 s45, s39, 0xa000
	global_load_lds_dwordx4 v[6:7], off
	v_lshl_add_u64 v[2:3], v[2:3], 0, s[12:13]
	s_mov_b32 m0, s44
	s_add_u32 s20, s30, 0x40080
	global_load_lds_dwordx4 v[2:3], off
	v_lshl_add_u64 v[2:3], v[4:5], 0, s[12:13]
	s_mov_b32 m0, s45
	s_addc_u32 s21, s31, 0
	global_load_lds_dwordx4 v[2:3], off
	s_add_i32 m0, s39, 0x1c000
	v_lshl_add_u64 v[2:3], s[20:21], 0, v[132:133]
	global_load_lds_dwordx4 v[2:3], off
	v_lshl_add_u64 v[2:3], s[20:21], 0, v[136:137]
	s_add_i32 m0, s39, 0x1e000
	v_lshlrev_b32_e32 v5, 2, v0
	global_load_lds_dwordx4 v[2:3], off
	v_and_b32_e32 v3, 24, v14
	v_and_b32_e32 v2, 15, v0
	v_lshlrev_b32_e32 v4, 1, v3
	v_lshl_or_b32 v1, s1, 6, v2
	v_lshl_or_b32 v2, v2, 6, v4
	v_and_b32_e32 v5, 32, v5
	s_sext_i32_i8 s5, s0
	v_bitop3_b32 v2, v2, s19, v5 bitop3:0xde
	v_lshlrev_b32_e32 v5, 6, v0
	s_movk_i32 s0, 0x3c0
	v_and_or_b32 v4, v5, s0, v4
	s_waitcnt vmcnt(8)
	v_and_b32_e32 v5, 32, v40
	v_or_b32_e32 v153, s22, v3
	v_lshlrev_b32_e32 v3, 8, v0
	v_bitop3_b32 v152, s23, v4, v5 bitop3:0xf6
	v_and_b32_e32 v3, 0x18000, v3
	v_lshlrev_b32_e32 v4, 11, v12
	v_or3_b32 v3, v10, v3, v4
	v_add_u32_e32 v138, v3, v11
	v_lshlrev_b32_e32 v3, 4, v13
	v_and_b32_e32 v3, 0x38000, v3
	s_mov_b64 s[0:1], 0x40080
	s_waitcnt vmcnt(6)
	s_cmpk_lt_u32 s18, 0x100
	v_or3_b32 v3, v10, v3, v4
	s_cselect_b64 s[18:19], -1, 0
	v_lshl_add_u64 v[140:141], v[138:139], 0, s[0:1]
	v_add_u32_e32 v138, v3, v11
	s_add_i32 s47, 0, 0x10000
	s_add_i32 s48, 0, 0x14000
	s_ashr_i32 s46, s88, 31
	v_lshl_add_u64 v[142:143], v[138:139], 0, s[0:1]
	v_mov_b64_e32 v[144:145], 0x100
	v_mov_b64_e32 v[146:147], 0xff
	v_add_u32_e32 v154, s47, v152
	v_add_u32_e32 v155, s48, v152
	v_add_u32_e32 v156, 0, v2
	v_mov_b32_e32 v157, 0x358637bd
	s_mov_b32 s49, 0xf800000
	v_mov_b32_e32 v158, 0x260
	s_barrier
	s_branch .LBB0_1316

.LBB0_1486:
	s_mov_b64 s[18:19], 0x80
	s_and_b32 s46, s1, 3
	s_add_i32 m0, s42, 0x18000
	v_lshl_add_u64 v[8:9], v[8:9], 0, s[18:19]
	s_lshl_b32 s1, s0, 13
	s_lshl_b32 s21, s46, 12
	s_waitcnt vmcnt(2)
	s_barrier
	global_load_lds_dwordx4 v[8:9], off
	v_lshl_add_u64 v[6:7], v[6:7], 0, s[18:19]
	s_add_i32 m0, s42, 0x1a000
	s_add_i32 s47, s42, 0x8000
	s_add_i32 s48, s42, 0xa000
	global_load_lds_dwordx4 v[6:7], off
	v_lshl_add_u64 v[2:3], v[2:3], 0, s[18:19]
	s_mov_b32 m0, s47
	s_add_u32 s4, s36, 0x40080
	global_load_lds_dwordx4 v[2:3], off
	v_lshl_add_u64 v[2:3], v[4:5], 0, s[18:19]
	s_mov_b32 m0, s48
	s_addc_u32 s5, s37, 0
	global_load_lds_dwordx4 v[2:3], off
	s_add_i32 m0, s42, 0x1c000
	v_lshl_add_u64 v[2:3], s[4:5], 0, v[132:133]
	global_load_lds_dwordx4 v[2:3], off
	v_lshl_add_u64 v[2:3], s[4:5], 0, v[136:137]
	s_add_i32 m0, s42, 0x1e000
	s_waitcnt vmcnt(7)
	v_lshl_or_b32 v150, s0, 6, v43
	global_load_lds_dwordx4 v[2:3], off
	v_and_b32_e32 v2, 3, v44
	v_lshlrev_b32_e32 v4, 6, v43
	v_lshlrev_b32_e32 v5, 4, v2
	s_movk_i32 s0, 0x3c0
	v_lshlrev_b32_e32 v6, 2, v43
	v_and_or_b32 v4, v4, s0, v5
	v_and_b32_e32 v6, 32, v6
	v_bitop3_b32 v4, v4, s1, v6 bitop3:0xde
	v_lshlrev_b32_e32 v6, 6, v0
	v_lshlrev_b32_e32 v3, 3, v2
	v_and_or_b32 v5, v6, s0, v5
	v_cmp_eq_u32_e64 s[0:1], 0, v2
	v_lshlrev_b32_e32 v2, 8, v0
	v_and_b32_e32 v6, 32, v42
	v_lshl_or_b32 v152, s46, 5, v3
	v_and_b32_e32 v2, 0x18000, v2
	v_lshlrev_b32_e32 v3, 11, v11
	v_bitop3_b32 v151, s21, v5, v6 bitop3:0xf6
	v_or3_b32 v2, v10, v2, v3
	v_and_b32_e32 v5, 64, v0
	s_mov_b32 s4, 0x40080
	v_or3_b32 v138, v2, v5, s4
	v_lshlrev_b32_e32 v2, 4, v12
	v_and_b32_e32 v2, 0x38000, v2
	s_waitcnt vmcnt(6)
	s_cmpk_lt_u32 s20, 0x100
	v_or3_b32 v2, v10, v2, v3
	v_lshrrev_b32_e32 v3, 4, v12
	s_cselect_b64 s[20:21], -1, 0
	v_and_b32_e32 v3, 64, v3
	s_add_i32 s51, 0, 0x10000
	s_add_i32 s52, 0, 0x14000
	s_ashr_i32 s49, s88, 31
	s_ashr_i32 s50, s2, 31
	v_mov_b32_e32 v139, v133
	v_or3_b32 v140, v2, v3, s4
	v_mov_b32_e32 v141, v133
	v_mov_b64_e32 v[142:143], 0x100
	v_mov_b64_e32 v[144:145], 0xff
	v_add_u32_e32 v153, s51, v151
	v_add_u32_e32 v154, s52, v151
	v_add_u32_e32 v155, 0, v4
	v_mbcnt_hi_u32_b32 v156, -1, v1
	s_mov_b32 s53, 0
	s_barrier
	s_branch .LBB0_1489
